# retention loop half-step 1: state-update K^T reads issued early into dedicated registers (state offsets recomputed at unit exit), lgkmcnt recounted
# baseline (speedup 1.0000x reference)
.LBB0_1370:
	s_add_i32 s1, s57, -1
	s_waitcnt vmcnt(7)
	ds_write_b128 v175, v[72:75]
	ds_write_b128 v175, v[68:71] offset:8704
	ds_write_b128 v175, v[64:67] offset:17408
	v_cndmask_b32_e32 v65, v180, v173, vcc
	v_xor_b32_e32 v66, 0xffffffef, v173
	v_xor_b32_e32 v70, 0xffffffcf, v173
	s_min_u32 s18, s1, s0
	v_add_u32_e32 v69, 48, v173
	v_xor_b32_e32 v67, 0xffffffdf, v173
	v_add_u32_e32 v71, s55, v66
	v_add_u32_e32 v66, s56, v65
	v_add_u32_e32 v70, s55, v70
	v_lshl_add_u32 v73, s18, 5, v174
	v_add_u32_e32 v64, 16, v173
	v_add_u32_e32 v68, 32, v173
	v_add_u32_e32 v65, s55, v67
	v_ashrrev_i32_e32 v67, 31, v66
	v_cndmask_b32_e32 v69, v70, v69, vcc
	v_xad_u32 v70, v73, -1, s55
	v_cndmask_b32_e32 v71, v71, v64, vcc
	v_cndmask_b32_e32 v68, v65, v68, vcc
	v_lshlrev_b64 v[64:65], 11, v[66:67]
	v_cndmask_b32_e32 v67, v70, v73, vcc
	s_min_u32 s42, s57, s0
	v_lshl_add_u64 v[242:243], v[170:171], 0, v[64:65]
	v_add_u32_e32 v64, s56, v67
	v_lshl_add_u32 v72, s42, 5, v174
	v_ashrrev_i32_e32 v65, 31, v64
	v_cvt_pk_bf16_f32 v60, v44, v45
	v_cvt_pk_bf16_f32 v61, v46, v47
	v_cvt_pk_bf16_f32 v62, v40, v41
	v_cvt_pk_bf16_f32 v63, v42, v43
	v_xad_u32 v74, v72, -1, s55
	v_lshlrev_b64 v[64:65], 13, v[64:65]
	v_cndmask_b32_e32 v66, v74, v72, vcc
	v_or_b32_e32 v64, v64, v181
	v_add_u32_e32 v238, s56, v68
	v_add_u32_e32 v240, s56, v69
	v_add_u32_e32 v244, s56, v66
	v_lshl_add_u64 v[66:67], s[36:37], 0, v[64:65]
	v_lshl_add_u64 v[68:69], s[38:39], 0, v[64:65]
	v_lshl_add_u64 v[64:65], s[40:41], 0, v[64:65]
	v_add_u32_e32 v0, 0x1000, v178
	v_add_u32_e32 v1, 0x2000, v179
	v_add_u32_e32 v182, 0x3000, v179
	v_add_u32_e32 v236, s56, v71
	global_load_dwordx4 v[72:75], v[66:67], off
	s_nop 0
	global_load_dwordx4 v[68:71], v[68:69], off
	s_nop 0
	global_load_dwordx4 v[64:67], v[64:65], off
	s_waitcnt lgkmcnt(0)
	s_barrier
	ds_read_b64 v[188:189], v178
	ds_read_b64 v[190:191], v178 offset:32
	ds_read_b64 v[192:193], v0 offset:256
	ds_read_b64 v[194:195], v0 offset:288
	ds_read_b64 v[196:197], v0 offset:320
	ds_read_b64 v[198:199], v0 offset:352
	ds_read_b64 v[200:201], v1 offset:512
	ds_read_b64 v[202:203], v1 offset:544
	ds_read_b64 v[204:205], v182 offset:768
	ds_read_b64 v[206:207], v182 offset:800
	ds_read_b64_tr_b16 v[210:211], v176 offset:13056
	ds_read_b64_tr_b16 v[212:213], v177 offset:17408
	ds_read_b64_tr_b16 v[214:215], v177 offset:21760
	ds_read_b64_tr_b16 v[208:209], v176 offset:8704
	ds_read_b64_tr_b16 v[216:217], v176 offset:8736
	ds_read_b64_tr_b16 v[220:221], v176 offset:8768
	ds_read_b64_tr_b16 v[222:223], v176 offset:13120
	ds_read_b64_tr_b16 v[218:219], v176 offset:13088
	ds_read_b64_tr_b16 v[94:95], v176 offset:8928
	s_waitcnt lgkmcnt(7)
	v_lshlrev_b32_e32 v232, 16, v212
	v_and_b32_e32 v233, 0xffff0000, v212
	v_lshlrev_b32_e32 v234, 16, v213
	v_and_b32_e32 v235, 0xffff0000, v213
	s_waitcnt lgkmcnt(6)
	v_lshlrev_b32_e32 v246, 16, v214
	v_and_b32_e32 v247, 0xffff0000, v214
	v_lshlrev_b32_e32 v248, 16, v215
	v_and_b32_e32 v249, 0xffff0000, v215
	v_mov_b32_e32 v159, v158
	v_mfma_f32_16x16x32_bf16 v[226:229], v[60:63], v[192:195], 0
	ds_read_b64_tr_b16 v[78:79], v176 offset:8800
	ds_read_b64_tr_b16 v[80:81], v176 offset:13152
	v_mul_f32_e64 v232, v150, v232
	v_mul_f32_e64 v233, v151, v233
	v_pk_mul_f32 v[234:235], v[152:153], v[234:235]
	v_pk_mul_f32 v[44:45], v[164:165], v[44:45]
	v_mfma_f32_16x16x32_bf16 v[60:63], v[60:63], v[188:191], 0
	ds_read_b64_tr_b16 v[90:91], v176 offset:8832
	ds_read_b64_tr_b16 v[92:93], v176 offset:13184
	v_mul_f32_e64 v46, v158, v46
	v_mul_f32_e64 v47, v159, v47
	v_pk_mul_f32 v[40:41], v[164:165], v[40:41]
	v_pk_mul_f32 v[42:43], v[158:159], v[42:43]
	v_mfma_f32_16x16x32_bf16 v[188:191], v[200:203], v[188:191], 0
	ds_read_b64_tr_b16 v[82:83], v176 offset:8864
	ds_read_b64_tr_b16 v[84:85], v176 offset:13216
	v_cvt_pk_bf16_f32 v52, v36, v37
	v_cvt_pk_bf16_f32 v53, v38, v39
	v_cvt_pk_bf16_f32 v54, v32, v33
	v_mfma_f32_16x16x32_bf16 v[200:203], v[200:203], v[192:195], 0
	ds_read_b64_tr_b16 v[86:87], v176 offset:8896
	ds_read_b64_tr_b16 v[88:89], v176 offset:13248
	v_cvt_pk_bf16_f32 v55, v34, v35
	v_cvt_pk_bf16_f32 v56, v28, v29
	v_cvt_pk_bf16_f32 v57, v30, v31
	v_mfma_f32_16x16x32_bf16 v[192:195], v[204:207], v[192:195], 0
	ds_read_b64_tr_b16 v[96:97], v176 offset:13280
	v_mul_f32_e64 v206, v154, v246
	v_mul_f32_e64 v207, v155, v247
	v_pk_mul_f32 v[246:247], v[156:157], v[248:249]
	v_cvt_pk_bf16_f32 v204, v232, v233
	v_cvt_pk_bf16_f32 v205, v234, v235
	v_cvt_pk_bf16_f32 v206, v206, v207
	v_cvt_pk_bf16_f32 v207, v246, v247
	v_pk_mul_f32 v[36:37], v[164:165], v[36:37]
	v_pk_mul_f32 v[32:33], v[164:165], v[32:33]
	s_waitcnt lgkmcnt(14)
	v_mfma_f32_16x16x32_bf16 v[44:47], v[208:211], v[204:207], v[44:47]
	v_pk_mul_f32 v[28:29], v[164:165], v[28:29]
	v_pk_mul_f32 v[38:39], v[158:159], v[38:39]
	s_waitcnt lgkmcnt(10)
	v_mfma_f32_16x16x32_bf16 v[40:43], v[216:219], v[204:207], v[40:43]
	v_pk_mul_f32 v[34:35], v[158:159], v[34:35]
	v_pk_mul_f32 v[30:31], v[158:159], v[30:31]
	v_mfma_f32_16x16x32_bf16 v[36:39], v[220:223], v[204:207], v[36:39]
	v_ashrrev_i32_e32 v245, 31, v244
	v_ashrrev_i32_e32 v237, 31, v236
	v_cvt_pk_bf16_f32 v58, v24, v25
	s_waitcnt lgkmcnt(7)
	v_mfma_f32_16x16x32_bf16 v[32:35], v[78:81], v[204:207], v[32:35]
	v_cvt_pk_bf16_f32 v59, v26, v27
	s_waitcnt lgkmcnt(5)
	v_mfma_f32_16x16x32_bf16 v[220:223], v[90:93], v[204:207], v[28:31]
	v_cvt_pk_bf16_f32 v48, v20, v21
	v_cvt_pk_bf16_f32 v49, v22, v23
	v_lshlrev_b64 v[28:29], 13, v[244:245]
	v_cvt_pk_bf16_f32 v50, v16, v17
	v_cvt_pk_bf16_f32 v51, v18, v19
	v_pk_mul_f32 v[24:25], v[164:165], v[24:25]
	v_pk_mul_f32 v[20:21], v[164:165], v[20:21]
	v_pk_mul_f32 v[16:17], v[164:165], v[16:17]
	v_pk_mul_f32 v[26:27], v[158:159], v[26:27]
	v_pk_mul_f32 v[22:23], v[158:159], v[22:23]
	v_pk_mul_f32 v[18:19], v[158:159], v[18:19]
	v_ashrrev_i32_e32 v239, 31, v238
	v_ashrrev_i32_e32 v241, 31, v240
	v_lshlrev_b64 v[236:237], 11, v[236:237]
	v_or_b32_e32 v28, v28, v181
	v_lshlrev_b64 v[246:247], 11, v[238:239]
	v_lshlrev_b64 v[248:249], 11, v[240:241]
	s_waitcnt lgkmcnt(3)
	v_mfma_f32_16x16x32_bf16 v[216:219], v[82:85], v[204:207], v[24:27]
	v_lshl_add_u64 v[234:235], v[170:171], 0, v[236:237]
	v_lshl_add_u64 v[236:237], s[36:37], 0, v[28:29]
	v_lshl_add_u64 v[238:239], s[38:39], 0, v[28:29]
	s_waitcnt lgkmcnt(1)
	v_mfma_f32_16x16x32_bf16 v[208:211], v[86:89], v[204:207], v[20:23]
	ds_read_b64 v[24:25], v1 offset:576
	ds_read_b64 v[26:27], v1 offset:608
	v_lshl_add_u64 v[240:241], s[40:41], 0, v[28:29]
	ds_read_b64 v[28:29], v182 offset:832
	ds_read_b64 v[30:31], v182 offset:864
	s_waitcnt lgkmcnt(4)
	v_mfma_f32_16x16x32_bf16 v[204:207], v[94:97], v[204:207], v[16:19]
	v_mov_b32_e32 v3, v2
	v_add_u32_e32 v183, 0x6000, v178
	v_add_u32_e32 v184, 0x7000, v178
	ds_read_b64 v[16:17], v178 offset:64
	ds_read_b64 v[18:19], v178 offset:96
	v_mfma_f32_16x16x32_bf16 v[226:229], v[52:55], v[196:199], v[226:229]
	v_add_u32_e32 v185, 0x8800, v179
	v_add_u32_e32 v186, 0x9800, v179
	s_add_i32 s57, s57, 2
	s_waitcnt lgkmcnt(0)
	v_mfma_f32_16x16x32_bf16 v[20:23], v[52:55], v[16:19], v[60:63]
	ds_read_b64 v[52:53], v0 offset:384
	ds_read_b64 v[54:55], v0 offset:416
	s_nop 1
	ds_read_b64 v[60:61], v178 offset:128
	ds_read_b64 v[62:63], v178 offset:160
	v_add_u32_e32 v173, 64, v173
	v_subrev_u32_e32 v180, 64, v180
	v_mfma_f32_16x16x32_bf16 v[16:19], v[24:27], v[16:19], v[188:191]
	s_cmp_ge_u32 s1, s58
	v_mfma_f32_16x16x32_bf16 v[24:27], v[24:27], v[196:199], v[200:203]
	v_mfma_f32_16x16x32_bf16 v[28:31], v[28:31], v[196:199], v[192:195]
	s_nop 2
	ds_read_b64 v[192:193], v1 offset:640
	ds_read_b64 v[194:195], v1 offset:672
	ds_read_b64 v[196:197], v178 offset:192
	ds_read_b64 v[198:199], v178 offset:224
	ds_read_b64 v[200:201], v0 offset:448
	ds_read_b64 v[202:203], v0 offset:480
	s_waitcnt lgkmcnt(8)
	v_mfma_f32_16x16x32_bf16 v[188:191], v[56:59], v[52:55], v[226:229]
	s_waitcnt lgkmcnt(6)
	v_mfma_f32_16x16x32_bf16 v[20:23], v[56:59], v[60:63], v[20:23]
	ds_read_b64 v[56:57], v182 offset:896
	ds_read_b64 v[58:59], v182 offset:928
	ds_read_b64 v[226:227], v1 offset:704
	ds_read_b64 v[228:229], v1 offset:736
	ds_read_b64 v[230:231], v182 offset:960
	ds_read_b64 v[232:233], v182 offset:992
	s_waitcnt vmcnt(5)
	ds_write_b128 v175, v[12:15] offset:26112
	ds_write_b128 v175, v[8:11] offset:34816
	ds_write_b128 v175, v[4:7] offset:43520
	s_waitcnt lgkmcnt(13)
	v_mfma_f32_16x16x32_bf16 v[16:19], v[192:195], v[60:63], v[16:19]
	v_mfma_f32_16x16x32_bf16 v[4:7], v[192:195], v[52:55], v[24:27]
	s_waitcnt lgkmcnt(7)
	v_mfma_f32_16x16x32_bf16 v[8:11], v[56:59], v[52:55], v[28:31]
	s_nop 0
	v_cvt_pk_bf16_f32 v24, v44, v45
	v_cvt_pk_bf16_f32 v25, v46, v47
	v_cvt_pk_bf16_f32 v26, v40, v41
	s_waitcnt lgkmcnt(5)
	v_mfma_f32_16x16x32_bf16 v[16:19], v[226:229], v[196:199], v[16:19]
	v_mul_f32_e64 v28, v164, v44
	v_mul_f32_e64 v29, v165, v45
	v_cvt_pk_bf16_f32 v27, v42, v43
	v_pk_mul_f32 v[30:31], v[158:159], v[46:47]
	v_mfma_f32_16x16x32_bf16 v[4:7], v[226:229], v[200:203], v[4:7]
	v_cvt_pk_bf16_f32 v52, v36, v37
	s_nop 1
	v_pk_mul_f32 v[18:19], v[146:147], v[18:19]
	v_pk_mul_f32 v[0:1], v[142:143], v[16:17]
	s_waitcnt lgkmcnt(3)
	v_mfma_f32_16x16x32_bf16 v[8:11], v[230:233], v[200:203], v[8:11]
	v_cvt_pk_bf16_f32 v0, v0, v1
	v_pk_mul_f32 v[6:7], v[148:149], v[6:7]
	v_pk_mul_f32 v[4:5], v[144:145], v[4:5]
	v_cvt_pk_bf16_f32 v1, v18, v19
	v_cvt_pk_bf16_f32 v4, v4, v5
	s_nop 2
	v_pk_mul_f32 v[16:17], v[146:147], v[10:11]
	v_pk_mul_f32 v[44:45], v[142:143], v[8:9]
	v_cvt_pk_bf16_f32 v5, v6, v7
	v_cvt_pk_bf16_f32 v6, v44, v45
	v_cvt_pk_bf16_f32 v7, v16, v17
	v_mfma_f32_16x16x32_bf16 v[12:15], v[48:51], v[200:203], v[188:191]
	v_cvt_pk_bf16_f32 v53, v38, v39
	v_pk_mul_f32 v[38:39], v[158:159], v[38:39]
	v_pk_mul_f32 v[36:37], v[164:165], v[36:37]
	v_mfma_f32_16x16x32_bf16 v[20:23], v[48:51], v[196:199], v[20:23]
	v_cvt_pk_bf16_f32 v54, v32, v33
	v_cvt_pk_bf16_f32 v55, v34, v35
	v_pk_mul_f32 v[42:43], v[158:159], v[42:43]
	v_mfma_f32_16x16x32_bf16 v[8:11], v[212:215], v[0:3], 0
	v_mul_f32_e64 v40, v164, v40
	v_mul_f32_e64 v41, v165, v41
	v_pk_mul_f32 v[34:35], v[158:159], v[34:35]
	v_pk_mul_f32 v[32:33], v[164:165], v[32:33]
	v_mfma_f32_16x16x32_bf16 v[4:7], v[212:215], v[4:7], 0
	v_mul_f32_e64 v50, v158, v222
	v_mul_f32_e64 v51, v159, v223
	s_nop 0
	v_pk_fma_f32 v[8:9], v[162:163], v[20:21], v[8:9]
	v_pk_mul_f32 v[48:49], v[164:165], v[220:221]
	v_cvt_pk_bf16_f32 v8, v8, v9
	v_cvt_pk_bf16_f32 v56, v220, v221
	s_nop 0
	v_pk_fma_f32 v[0:1], v[166:167], v[14:15], v[6:7]
	v_pk_fma_f32 v[6:7], v[168:169], v[22:23], v[10:11]
	v_pk_fma_f32 v[4:5], v[160:161], v[12:13], v[4:5]
	v_cvt_pk_bf16_f32 v9, v6, v7
	v_cvt_pk_bf16_f32 v4, v4, v5
	v_cvt_pk_bf16_f32 v5, v0, v1
	global_store_dwordx2 v[242:243], v[8:9], off
	global_store_dwordx2 v[234:235], v[4:5], off
	global_load_dwordx4 v[12:15], v[236:237], off
	s_nop 0
	global_load_dwordx4 v[8:11], v[238:239], off
	global_load_dwordx4 v[4:7], v[240:241], off
	s_waitcnt lgkmcnt(0)
	s_barrier
	ds_read_b64 v[16:17], v183 offset:1536
	ds_read_b64 v[18:19], v183 offset:1568
	ds_read_b64 v[20:21], v184 offset:1792
	ds_read_b64 v[22:23], v184 offset:1824
	ds_read_b64 v[60:61], v184 offset:1856
	ds_read_b64 v[62:63], v184 offset:1888
	ds_read_b64 v[44:45], v185
	ds_read_b64 v[46:47], v185 offset:32
	ds_read_b64 v[188:189], v186 offset:256
	ds_read_b64 v[190:191], v186 offset:288
	ds_read_b64_tr_b16 v[194:195], v176 offset:39168
	ds_read_b64_tr_b16 v[196:197], v177 offset:43520
	ds_read_b64_tr_b16 v[198:199], v177 offset:47872
	ds_read_b64_tr_b16 v[192:193], v176 offset:34816
	ds_read_b64_tr_b16 v[200:201], v176 offset:34848
	ds_read_b64_tr_b16 v[212:213], v176 offset:34880
	ds_read_b64_tr_b16 v[214:215], v176 offset:39232
	s_waitcnt lgkmcnt(13)
	v_mfma_f32_16x16x32_bf16 v[226:229], v[24:27], v[20:23], 0
	s_waitcnt lgkmcnt(5)
	v_lshlrev_b32_e32 v0, 16, v196
	v_and_b32_e32 v1, 0xffff0000, v196
	v_pk_mul_f32 v[0:1], v[150:151], v[0:1]
	v_mfma_f32_16x16x32_bf16 v[234:237], v[24:27], v[16:19], 0
	v_lshlrev_b32_e32 v24, 16, v197
	v_and_b32_e32 v25, 0xffff0000, v197
	v_pk_mul_f32 v[24:25], v[152:153], v[24:25]
	v_mfma_f32_16x16x32_bf16 v[238:241], v[44:47], v[16:19], 0
	s_waitcnt lgkmcnt(4)
	v_lshlrev_b32_e32 v16, 16, v198
	v_and_b32_e32 v17, 0xffff0000, v198
	v_lshlrev_b32_e32 v18, 16, v199
	v_and_b32_e32 v19, 0xffff0000, v199
	v_mfma_f32_16x16x32_bf16 v[242:245], v[44:47], v[20:23], 0
	ds_read_b64_tr_b16 v[202:203], v176 offset:39200
	ds_read_b64_tr_b16 v[230:231], v176 offset:35040
	v_cvt_pk_bf16_f32 v57, v222, v223
	v_cvt_pk_bf16_f32 v58, v216, v217
	v_mfma_f32_16x16x32_bf16 v[188:191], v[188:191], v[20:23], 0
	v_mul_f32_e64 v20, v154, v16
	v_mul_f32_e64 v21, v155, v17
	v_pk_mul_f32 v[22:23], v[156:157], v[18:19]
	v_cvt_pk_bf16_f32 v16, v0, v1
	v_cvt_pk_bf16_f32 v17, v24, v25
	v_cvt_pk_bf16_f32 v18, v20, v21
	v_cvt_pk_bf16_f32 v19, v22, v23
	ds_read_b64_tr_b16 v[22:23], v176 offset:39264
	ds_read_b64_tr_b16 v[20:21], v176 offset:34912
	ds_read_b64_tr_b16 v[24:25], v176 offset:34944
	s_waitcnt lgkmcnt(8)
	v_mfma_f32_16x16x32_bf16 v[44:47], v[192:195], v[16:19], v[28:31]
	ds_read_b64_tr_b16 v[192:193], v176 offset:34976
	ds_read_b64_tr_b16 v[26:27], v176 offset:39296
	ds_read_b64_tr_b16 v[194:195], v176 offset:39328
	ds_read_b64_tr_b16 v[232:233], v176 offset:39392
	v_cvt_pk_bf16_f32 v59, v218, v219
	s_waitcnt lgkmcnt(9)
	v_mfma_f32_16x16x32_bf16 v[36:39], v[212:215], v[16:19], v[36:39]
	ds_read_b64_tr_b16 v[212:213], v176 offset:35008
	ds_read_b64_tr_b16 v[214:215], v176 offset:39360
	s_waitcnt lgkmcnt(10)
	v_mfma_f32_16x16x32_bf16 v[40:43], v[200:203], v[16:19], v[40:43]
	v_mul_f32_e64 v202, v158, v218
	v_mul_f32_e64 v203, v159, v219
	v_pk_mul_f32 v[200:201], v[164:165], v[216:217]
	ds_read_b64 v[216:217], v183 offset:1664
	ds_read_b64 v[218:219], v183 offset:1696
	s_waitcnt lgkmcnt(9)
	v_mfma_f32_16x16x32_bf16 v[32:35], v[20:23], v[16:19], v[32:35]
	v_mul_f32_e64 v22, v158, v210
	v_mul_f32_e64 v23, v159, v211
	v_pk_mul_f32 v[20:21], v[164:165], v[208:209]
	s_waitcnt lgkmcnt(6)
	v_mfma_f32_16x16x32_bf16 v[28:31], v[24:27], v[16:19], v[48:51]
	s_waitcnt lgkmcnt(5)
	v_mfma_f32_16x16x32_bf16 v[24:27], v[192:195], v[16:19], v[200:203]
	ds_read_b64 v[192:193], v185 offset:64
	ds_read_b64 v[194:195], v185 offset:96
	v_pk_mul_f32 v[50:51], v[158:159], v[206:207]
	v_pk_mul_f32 v[48:49], v[164:165], v[204:205]
	s_waitcnt lgkmcnt(4)
	v_mfma_f32_16x16x32_bf16 v[20:23], v[212:215], v[16:19], v[20:23]
	ds_read_b64 v[212:213], v186 offset:320
	ds_read_b64 v[214:215], v186 offset:352
	v_cvt_pk_bf16_f32 v202, v204, v205
	v_cvt_pk_bf16_f32 v203, v206, v207
	v_mfma_f32_16x16x32_bf16 v[16:19], v[230:233], v[16:19], v[48:51]
	ds_read_b64 v[204:205], v183 offset:1728
	ds_read_b64 v[206:207], v183 offset:1760
	v_cvt_pk_bf16_f32 v200, v208, v209
	v_cvt_pk_bf16_f32 v201, v210, v211
	ds_read_b64 v[48:49], v183 offset:1600
	ds_read_b64 v[50:51], v183 offset:1632
	v_mfma_f32_16x16x32_bf16 v[226:229], v[52:55], v[60:63], v[226:229]
	s_waitcnt lgkmcnt(0)
	v_mfma_f32_16x16x32_bf16 v[52:55], v[52:55], v[48:51], v[234:237]
	v_mfma_f32_16x16x32_bf16 v[48:51], v[192:195], v[48:51], v[238:241]
	v_mfma_f32_16x16x32_bf16 v[192:195], v[192:195], v[60:63], v[242:245]
	v_mfma_f32_16x16x32_bf16 v[60:63], v[212:215], v[60:63], v[188:191]
	s_nop 2
	ds_read_b64 v[188:189], v184 offset:1920
	ds_read_b64 v[190:191], v184 offset:1952
	s_waitcnt lgkmcnt(0)
	v_mfma_f32_16x16x32_bf16 v[212:215], v[56:59], v[188:191], v[226:229]
	v_mfma_f32_16x16x32_bf16 v[52:55], v[56:59], v[216:219], v[52:55]
	ds_read_b64 v[56:57], v185 offset:128
	ds_read_b64 v[58:59], v185 offset:160
	s_waitcnt lgkmcnt(0)
	v_mfma_f32_16x16x32_bf16 v[48:51], v[56:59], v[216:219], v[48:51]
	v_mfma_f32_16x16x32_bf16 v[56:59], v[56:59], v[188:191], v[192:195]
	s_nop 2
	ds_read_b64 v[192:193], v186 offset:384
	ds_read_b64 v[194:195], v186 offset:416
	s_waitcnt lgkmcnt(0)
	v_mfma_f32_16x16x32_bf16 v[60:63], v[192:195], v[188:191], v[60:63]
	ds_read_b64 v[188:189], v184 offset:1984
	ds_read_b64 v[190:191], v184 offset:2016
	ds_read_b64 v[182:183], v185 offset:192
	ds_read_b64 v[184:185], v185 offset:224
	s_waitcnt lgkmcnt(0)
	v_mfma_f32_16x16x32_bf16 v[48:51], v[182:185], v[204:207], v[48:51]
	s_nop 7
	v_pk_mul_f32 v[50:51], v[146:147], v[50:51]
	v_mfma_f32_16x16x32_bf16 v[56:59], v[182:185], v[188:191], v[56:59]
	ds_read_b64 v[182:183], v186 offset:448
	ds_read_b64 v[184:185], v186 offset:480
	v_pk_mul_f32 v[0:1], v[142:143], v[48:49]
	s_waitcnt lgkmcnt(0)
	v_mfma_f32_16x16x32_bf16 v[60:63], v[182:185], v[188:191], v[60:63]
	s_nop 3
	v_mul_f32_e64 v182, v148, v58
	v_mul_f32_e64 v183, v149, v59
	v_pk_mul_f32 v[48:49], v[144:145], v[56:57]
	v_cvt_pk_bf16_f32 v0, v0, v1
	v_pk_mul_f32 v[62:63], v[146:147], v[62:63]
	v_pk_mul_f32 v[60:61], v[142:143], v[60:61]
	v_cvt_pk_bf16_f32 v1, v50, v51
	v_cvt_pk_bf16_f32 v48, v48, v49
	v_cvt_pk_bf16_f32 v49, v182, v183
	v_cvt_pk_bf16_f32 v50, v60, v61
	v_cvt_pk_bf16_f32 v51, v62, v63
	v_mfma_f32_16x16x32_bf16 v[192:195], v[200:203], v[188:191], v[212:215]
	v_mfma_f32_16x16x32_bf16 v[52:55], v[200:203], v[204:207], v[52:55]
	v_lshl_add_u64 v[200:201], v[170:171], 0, v[246:247]
	v_lshl_add_u64 v[202:203], v[170:171], 0, v[248:249]
	v_mfma_f32_16x16x32_bf16 v[56:59], v[196:199], v[0:3], 0
	v_mfma_f32_16x16x32_bf16 v[48:51], v[196:199], v[48:51], 0
	s_nop 6
	v_fma_f32 v52, v162, v52, v56
	v_fma_f32 v53, v163, v53, v57
	v_pk_fma_f32 v[0:1], v[166:167], v[194:195], v[50:51]
	v_pk_fma_f32 v[50:51], v[168:169], v[54:55], v[58:59]
	v_pk_fma_f32 v[48:49], v[160:161], v[192:193], v[48:49]
	v_cvt_pk_bf16_f32 v52, v52, v53
	v_cvt_pk_bf16_f32 v53, v50, v51
	v_cvt_pk_bf16_f32 v48, v48, v49
	v_cvt_pk_bf16_f32 v49, v0, v1
	global_store_dwordx2 v[200:201], v[52:53], off
	global_store_dwordx2 v[202:203], v[48:49], off
	s_cbranch_scc0 .LBB0_1370
	s_andn2_b64 vcc, exec, s[6:7]
	s_cbranch_vccnz .LBB0_1354
	s_add_u32 s0, s28, s14
	s_addc_u32 s1, s29, s15
	v_lshl_add_u64 v[0:1], v[112:113], 2, s[0:1]
	s_waitcnt vmcnt(2)
	v_mov_b32_e32 v7, 0
	v_lshl_add_u64 v[4:5], v[0:1], 0, v[76:77]
	global_store_dword v[4:5], v44, off nt
	v_or_b32_e32 v6, 0x4000, v76
	v_lshl_add_u64 v[4:5], v[0:1], 0, v[6:7]
	global_store_dword v[4:5], v45, off nt
	v_or_b32_e32 v6, 0x200, v76
	v_lshl_add_u64 v[4:5], v[0:1], 0, v[6:7]
	global_store_dword v[4:5], v46, off nt
	v_or_b32_e32 v6, 0x4200, v76
	v_lshl_add_u64 v[4:5], v[0:1], 0, v[6:7]
	global_store_dword v[4:5], v47, off nt
	v_or_b32_e32 v6, 0x1000, v76
	v_lshl_add_u64 v[4:5], v[0:1], 0, v[6:7]
	global_store_dword v[4:5], v40, off nt
	v_or_b32_e32 v6, 0x5000, v76
	v_lshl_add_u64 v[4:5], v[0:1], 0, v[6:7]
	global_store_dword v[4:5], v41, off nt
	v_or_b32_e32 v6, 0x1200, v76
	v_lshl_add_u64 v[4:5], v[0:1], 0, v[6:7]
	global_store_dword v[4:5], v42, off nt
	v_or_b32_e32 v6, 0x5200, v76
	v_lshl_add_u64 v[4:5], v[0:1], 0, v[6:7]
	global_store_dword v[4:5], v43, off nt
	v_or_b32_e32 v6, 0x2000, v76
	v_lshl_add_u64 v[4:5], v[0:1], 0, v[6:7]
	global_store_dword v[4:5], v36, off nt
	v_or_b32_e32 v6, 0x6000, v76
	v_lshl_add_u64 v[4:5], v[0:1], 0, v[6:7]
	global_store_dword v[4:5], v37, off nt
	v_or_b32_e32 v6, 0x2200, v76
	v_lshl_add_u64 v[4:5], v[0:1], 0, v[6:7]
	global_store_dword v[4:5], v38, off nt
	v_or_b32_e32 v6, 0x6200, v76
	v_lshl_add_u64 v[4:5], v[0:1], 0, v[6:7]
	global_store_dword v[4:5], v39, off nt
	v_or_b32_e32 v6, 0x3000, v76
	v_lshl_add_u64 v[4:5], v[0:1], 0, v[6:7]
	global_store_dword v[4:5], v32, off nt
	v_or_b32_e32 v6, 0x7000, v76
	v_lshl_add_u64 v[4:5], v[0:1], 0, v[6:7]
	global_store_dword v[4:5], v33, off nt
	v_or_b32_e32 v6, 0x3200, v76
	v_lshl_add_u64 v[4:5], v[0:1], 0, v[6:7]
	global_store_dword v[4:5], v34, off nt
	v_or_b32_e32 v6, 0x7200, v76
	v_lshl_add_u64 v[4:5], v[0:1], 0, v[6:7]
	global_store_dword v[4:5], v35, off nt
	v_or_b32_e32 v6, 0x8000, v76
	v_lshl_add_u64 v[4:5], v[0:1], 0, v[6:7]
	global_store_dword v[4:5], v28, off nt
	v_or_b32_e32 v6, 0xc000, v76
	v_lshl_add_u64 v[4:5], v[0:1], 0, v[6:7]
	global_store_dword v[4:5], v29, off nt
	v_or_b32_e32 v6, 0x8200, v76
	v_lshl_add_u64 v[4:5], v[0:1], 0, v[6:7]
	global_store_dword v[4:5], v30, off nt
	v_or_b32_e32 v6, 0xc200, v76
	v_lshl_add_u64 v[4:5], v[0:1], 0, v[6:7]
	global_store_dword v[4:5], v31, off nt
	v_or_b32_e32 v6, 0x9000, v76
	v_lshl_add_u64 v[4:5], v[0:1], 0, v[6:7]
	global_store_dword v[4:5], v24, off nt
	v_or_b32_e32 v6, 0xd000, v76
	v_lshl_add_u64 v[4:5], v[0:1], 0, v[6:7]
	global_store_dword v[4:5], v25, off nt
	v_or_b32_e32 v6, 0x9200, v76
	v_lshl_add_u64 v[4:5], v[0:1], 0, v[6:7]
	global_store_dword v[4:5], v26, off nt
	v_or_b32_e32 v6, 0xd200, v76
	v_lshl_add_u64 v[4:5], v[0:1], 0, v[6:7]
	global_store_dword v[4:5], v27, off nt
	v_or_b32_e32 v6, 0xa000, v76
	v_lshl_add_u64 v[4:5], v[0:1], 0, v[6:7]
	global_store_dword v[4:5], v20, off nt
	v_or_b32_e32 v6, 0xe000, v76
	v_lshl_add_u64 v[4:5], v[0:1], 0, v[6:7]
	global_store_dword v[4:5], v21, off nt
	v_or_b32_e32 v6, 0xa200, v76
	v_lshl_add_u64 v[4:5], v[0:1], 0, v[6:7]
	global_store_dword v[4:5], v22, off nt
	v_or_b32_e32 v6, 0xe200, v76
	v_lshl_add_u64 v[4:5], v[0:1], 0, v[6:7]
	global_store_dword v[4:5], v23, off nt
	v_or_b32_e32 v6, 0xb000, v76
	v_lshl_add_u64 v[4:5], v[0:1], 0, v[6:7]
	global_store_dword v[4:5], v16, off nt
	v_or_b32_e32 v6, 0xf000, v76
	v_lshl_add_u64 v[4:5], v[0:1], 0, v[6:7]
	global_store_dword v[4:5], v17, off nt
	v_or_b32_e32 v6, 0xb200, v76
	v_lshl_add_u64 v[4:5], v[0:1], 0, v[6:7]
	v_or_b32_e32 v6, 0xf200, v76
	v_lshl_add_u64 v[0:1], v[0:1], 0, v[6:7]
	global_store_dword v[4:5], v18, off nt
	global_store_dword v[0:1], v19, off nt
	s_branch .LBB0_1354
